# accumulator init with packed adds (two per group of four)
# speedup vs baseline: 1.0102x; 1.0018x over previous
; #define LAS __attribute__((address_space(3)))
; template <int MODE  > ...
;     ...
;     {
;         LAS bf16_t* kb = (LAS bf16_t*)(lds + A_KBUF) + cur * 64 * KPITCH;
;         *(LAS u32x4*)(kb + skey * KPITCH + schunk * 8) = kreg;
;         if (NEEDV) { LAS bf16_t* vb = (LAS bf16_t*)(lds + A_VBUF) + cur * 64 * VPITCH;
;             *(LAS u32x4*)(vb + skey * VPITCH + schunk * 8) = vreg; }
;     }
;     __syncthreads();
;     ...
;             { const float sl2 = sl + sl, sl3 = sl2 + sl;
; #pragma unroll
;               for (int g8 = 0; g8 < 4; ++g8) {
;                   const float b0 = __builtin_fmaf(sl, (float)(8 * g8), basef), b1 = __builtin_fmaf(sl, (float)(8 * g8 + 32), basef);
;                   s0[4 * g8] = b0; s0[4 * g8 + 1] = b0 + sl; s0[4 * g8 + 2] = b0 + sl2; s0[4 * g8 + 3] = b0 + sl3;
;                   s1[4 * g8] = b1; s1[4 * g8 + 1] = b1 + sl; s1[4 * g8 + 2] = b1 + sl2; s1[4 * g8 + 3] = b1 + sl3;
;               } }
.Lm0_pre_w:
	s_waitcnt lgkmcnt(0)
	ds_write_b128 v214, v[160:163]
	ds_write_b128 v215, v[164:167] offset:18432
	s_waitcnt lgkmcnt(0)
	s_barrier
	v_mov_b32_e32 v224, 0
	v_mov_b32_e32 v225, v190
	v_mov_b32_e32 v252, v191
	v_mov_b32_e32 v253, v187

; template <int MODE  > ...
;     ...
;             constexpr int STEP = CMPM ? 16 : 1;
;             const int Bint = CMPM ? (1024 * j + 31 - t + 64 * h) : (64 * j - t + 4 * h);
;             const float sl = slope2 * (float)STEP;
;             const float mref = st.m; const bool fresh = !(mref > -1e28f);
;             const float mest = fresh ? 0.f : mref;
;             const float basef = selbit ? (slope2 * (float)Bint - mest) : -1e30f;
;             int ptype;
;             if (MODE == 1) ptype = (j == cblk) ? 1 : 0;
;             else if (MODE == 2) ptype = (j == cblk) ? 1 : ((j == cblk - 8) ? 2 : 0);
;             else ptype = (64 * j + 63 <= 4 * cblk - 2) ? 0 : 1;
;             f32x16 s0, s1;
;             { const float sl2 = sl + sl, sl3 = sl2 + sl;
; #pragma unroll
;               for (int g8 = 0; g8 < 4; ++g8) {
;                   const float b0 = __builtin_fmaf(sl, (float)(8 * g8), basef), b1 = __builtin_fmaf(sl, (float)(8 * g8 + 32), basef);
;                   s0[4 * g8] = b0; s0[4 * g8 + 1] = b0 + sl; s0[4 * g8 + 2] = b0 + sl2; s0[4 * g8 + 3] = b0 + sl3;
;                   s1[4 * g8] = b1; s1[4 * g8 + 1] = b1 + sl; s1[4 * g8 + 2] = b1 + sl2; s1[4 * g8 + 3] = b1 + sl3;
;               } }
;             if (ptype == 1) {
;                 const float thr = 0.5f * slope2 - mest;
; #pragma unroll
;                 for (int i = 0; i < 16; ++i) { s0[i] = (s0[i] < thr) ? s0[i] : -1e30f; s1[i] = (s1[i] < thr) ? s1[i] : -1e30f; }
.Lm00_noload:
.Lm0_body0:
	ds_read_b128 v[80:83], v216
	ds_read_b128 v[84:87], v216 offset:4608
	ds_read_b128 v[88:91], v216 offset:32
	ds_read_b128 v[92:95], v216 offset:4640
	ds_read_b128 v[96:99], v216 offset:64
	ds_read_b128 v[100:103], v216 offset:4672
	ds_read_b128 v[104:107], v216 offset:96
	ds_read_b128 v[108:111], v216 offset:4704
	v_lshl_add_u32 v1, s90, 10, v217
	v_cvt_f32_i32_e32 v48, v1
	v_cmp_nlt_f32_e64 s[14:15], s71, v219
	s_lshl_b32 s17, s90, 6
	s_or_b32 s17, s17, 63
	s_cmp_le_i32 s17, s69
	v_cndmask_b32_e64 v1, v219, 0, s[14:15]
	v_fma_f32 v60, v186, v48, -v1
	v_fma_f32 v64, 0, v190, v60
	v_fmamk_f32 v68, v190, 0x41000000, v60
	v_fmamk_f32 v72, v190, 0x41800000, v60
	v_fmamk_f32 v76, v190, 0x41c00000, v60
	v_fmamk_f32 v48, v190, 0x42000000, v60
	v_fmamk_f32 v52, v190, 0x42200000, v60
	v_fmamk_f32 v56, v190, 0x42400000, v60
	v_fmac_f32_e32 v60, 0x42600000, v190
	v_pk_add_f32 v[66:67], v[252:253], v[64:65] op_sel_hi:[1,0]
	v_pk_add_f32 v[64:65], v[224:225], v[64:65] op_sel_hi:[1,0]
	v_pk_add_f32 v[70:71], v[252:253], v[68:69] op_sel_hi:[1,0]
	v_pk_add_f32 v[68:69], v[224:225], v[68:69] op_sel_hi:[1,0]
	v_pk_add_f32 v[74:75], v[252:253], v[72:73] op_sel_hi:[1,0]
	v_pk_add_f32 v[72:73], v[224:225], v[72:73] op_sel_hi:[1,0]
	v_pk_add_f32 v[78:79], v[252:253], v[76:77] op_sel_hi:[1,0]
	v_pk_add_f32 v[76:77], v[224:225], v[76:77] op_sel_hi:[1,0]
	v_pk_add_f32 v[50:51], v[252:253], v[48:49] op_sel_hi:[1,0]
	v_pk_add_f32 v[48:49], v[224:225], v[48:49] op_sel_hi:[1,0]
	v_pk_add_f32 v[54:55], v[252:253], v[52:53] op_sel_hi:[1,0]
	v_pk_add_f32 v[52:53], v[224:225], v[52:53] op_sel_hi:[1,0]
	v_pk_add_f32 v[58:59], v[252:253], v[56:57] op_sel_hi:[1,0]
	v_pk_add_f32 v[56:57], v[224:225], v[56:57] op_sel_hi:[1,0]
	v_pk_add_f32 v[62:63], v[252:253], v[60:61] op_sel_hi:[1,0]
	v_pk_add_f32 v[60:61], v[224:225], v[60:61] op_sel_hi:[1,0]
	s_cbranch_scc1 .Lm00_qk
	v_sub_f32_e32 v254, v189, v1
	v_cmp_lt_f32_e32 vcc, v64, v254
	s_nop 1
	v_cndmask_b32_e32 v64, v241, v64, vcc
	v_cmp_lt_f32_e32 vcc, v65, v254
	s_nop 1
	v_cndmask_b32_e32 v65, v241, v65, vcc
	v_cmp_lt_f32_e32 vcc, v66, v254
	s_nop 1
	v_cndmask_b32_e32 v66, v241, v66, vcc
	v_cmp_lt_f32_e32 vcc, v67, v254
	s_nop 1
	v_cndmask_b32_e32 v67, v241, v67, vcc
	v_cmp_lt_f32_e32 vcc, v68, v254
	s_nop 1
	v_cndmask_b32_e32 v68, v241, v68, vcc
	v_cmp_lt_f32_e32 vcc, v69, v254
	s_nop 1
	v_cndmask_b32_e32 v69, v241, v69, vcc
	v_cmp_lt_f32_e32 vcc, v70, v254
	s_nop 1
	v_cndmask_b32_e32 v70, v241, v70, vcc
	v_cmp_lt_f32_e32 vcc, v71, v254
	s_nop 1
	v_cndmask_b32_e32 v71, v241, v71, vcc
	v_cmp_lt_f32_e32 vcc, v72, v254
	s_nop 1
	v_cndmask_b32_e32 v72, v241, v72, vcc
	v_cmp_lt_f32_e32 vcc, v73, v254
	s_nop 1
	v_cndmask_b32_e32 v73, v241, v73, vcc
	v_cmp_lt_f32_e32 vcc, v74, v254
	s_nop 1
	v_cndmask_b32_e32 v74, v241, v74, vcc
	v_cmp_lt_f32_e32 vcc, v75, v254
	s_nop 1
	v_cndmask_b32_e32 v75, v241, v75, vcc
	v_cmp_lt_f32_e32 vcc, v76, v254
	s_nop 1
	v_cndmask_b32_e32 v76, v241, v76, vcc
	v_cmp_lt_f32_e32 vcc, v77, v254
	s_nop 1
	v_cndmask_b32_e32 v77, v241, v77, vcc
	v_cmp_lt_f32_e32 vcc, v78, v254
	s_nop 1
	v_cndmask_b32_e32 v78, v241, v78, vcc
	v_cmp_lt_f32_e32 vcc, v79, v254
	s_nop 1
	v_cndmask_b32_e32 v79, v241, v79, vcc
	v_cmp_lt_f32_e32 vcc, v48, v254
	s_nop 1
	v_cndmask_b32_e32 v48, v241, v48, vcc
	v_cmp_lt_f32_e32 vcc, v49, v254
	s_nop 1
	v_cndmask_b32_e32 v49, v241, v49, vcc
	v_cmp_lt_f32_e32 vcc, v50, v254
	s_nop 1
	v_cndmask_b32_e32 v50, v241, v50, vcc
	v_cmp_lt_f32_e32 vcc, v51, v254
	s_nop 1
	v_cndmask_b32_e32 v51, v241, v51, vcc
	v_cmp_lt_f32_e32 vcc, v52, v254
	s_nop 1
	v_cndmask_b32_e32 v52, v241, v52, vcc
	v_cmp_lt_f32_e32 vcc, v53, v254
	s_nop 1
	v_cndmask_b32_e32 v53, v241, v53, vcc
	v_cmp_lt_f32_e32 vcc, v54, v254
	s_nop 1
	v_cndmask_b32_e32 v54, v241, v54, vcc
	v_cmp_lt_f32_e32 vcc, v55, v254
	s_nop 1
	v_cndmask_b32_e32 v55, v241, v55, vcc
	v_cmp_lt_f32_e32 vcc, v56, v254
	s_nop 1
	v_cndmask_b32_e32 v56, v241, v56, vcc
	v_cmp_lt_f32_e32 vcc, v57, v254
	s_nop 1
	v_cndmask_b32_e32 v57, v241, v57, vcc
	v_cmp_lt_f32_e32 vcc, v58, v254
	s_nop 1
	v_cndmask_b32_e32 v58, v241, v58, vcc
	v_cmp_lt_f32_e32 vcc, v59, v254
	s_nop 1
	v_cndmask_b32_e32 v59, v241, v59, vcc
	v_cmp_lt_f32_e32 vcc, v60, v254
	s_nop 1
	v_cndmask_b32_e32 v60, v241, v60, vcc
	v_cmp_lt_f32_e32 vcc, v61, v254
	s_nop 1
	v_cndmask_b32_e32 v61, v241, v61, vcc
	v_cmp_lt_f32_e32 vcc, v62, v254
	s_nop 1
	v_cndmask_b32_e32 v62, v241, v62, vcc
	v_cmp_lt_f32_e32 vcc, v63, v254
	s_nop 1
	v_cndmask_b32_e32 v63, v241, v63, vcc

; #define LAS __attribute__((address_space(3)))
; template <int MODE  > ...
;     ...
;             const LAS bf16_t* kb = (const LAS bf16_t*)(lds + A_KBUF) + cur * 64 * KPITCH;
;             constexpr int STEP = CMPM ? 16 : 1;
;             const int Bint = CMPM ? (1024 * j + 31 - t + 64 * h) : (64 * j - t + 4 * h);
;             const float sl = slope2 * (float)STEP;
;             const float mref = st.m; const bool fresh = !(mref > -1e28f);
;             const float mest = fresh ? 0.f : mref;
;             const float basef = selbit ? (slope2 * (float)Bint - mest) : -1e30f;
;             int ptype;
;             if (MODE == 1) ptype = (j == cblk) ? 1 : 0;
;             else if (MODE == 2) ptype = (j == cblk) ? 1 : ((j == cblk - 8) ? 2 : 0);
;             else ptype = (64 * j + 63 <= 4 * cblk - 2) ? 0 : 1;
;             f32x16 s0, s1;
;             { const float sl2 = sl + sl, sl3 = sl2 + sl;
; #pragma unroll
;               for (int g8 = 0; g8 < 4; ++g8) {
;                   const float b0 = __builtin_fmaf(sl, (float)(8 * g8), basef), b1 = __builtin_fmaf(sl, (float)(8 * g8 + 32), basef);
;                   s0[4 * g8] = b0; s0[4 * g8 + 1] = b0 + sl; s0[4 * g8 + 2] = b0 + sl2; s0[4 * g8 + 3] = b0 + sl3;
;                   s1[4 * g8] = b1; s1[4 * g8 + 1] = b1 + sl; s1[4 * g8 + 2] = b1 + sl2; s1[4 * g8 + 3] = b1 + sl3;
;               } }
;             if (ptype == 1) {
;                 const float thr = 0.5f * slope2 - mest;
; #pragma unroll
;                 for (int i = 0; i < 16; ++i) { s0[i] = (s0[i] < thr) ? s0[i] : -1e30f; s1[i] = (s1[i] < thr) ? s1[i] : -1e30f; }
;             } else if (ptype == 2) {
;                 const float thr = -511.5f * slope2 - mest;
; #pragma unroll
;                 for (int i = 0; i < 16; ++i) { s0[i] = (s0[i] > thr) ? s0[i] : -1e30f; s1[i] = (s1[i] > thr) ? s1[i] : -1e30f; }
;             }
; #pragma unroll
;             for (int kk = 0; kk < 4; ++kk) {
;                 const bf16x8 k0 = *(const LAS bf16x8*)(kb + col * KPITCH + kk * 16 + h * 8);
;                 const bf16x8 k1 = *(const LAS bf16x8*)(kb + (32 + col) * KPITCH + kk * 16 + h * 8);
.Lm01_noload:
.Lm0_body1:
	ds_read_b128 v[80:83], v216 offset:9216
	ds_read_b128 v[84:87], v216 offset:13824
	ds_read_b128 v[88:91], v216 offset:9248
	ds_read_b128 v[92:95], v216 offset:13856
	ds_read_b128 v[96:99], v216 offset:9280
	ds_read_b128 v[100:103], v216 offset:13888
	ds_read_b128 v[104:107], v216 offset:9312
	ds_read_b128 v[108:111], v216 offset:13920
	v_lshl_add_u32 v1, s90, 10, v217
	v_cvt_f32_i32_e32 v48, v1
	v_cmp_nlt_f32_e64 s[14:15], s71, v219
	s_lshl_b32 s17, s90, 6
	s_or_b32 s17, s17, 63
	s_cmp_le_i32 s17, s69
	v_cndmask_b32_e64 v1, v219, 0, s[14:15]
	v_fma_f32 v60, v186, v48, -v1
	v_fma_f32 v64, 0, v190, v60
	v_fmamk_f32 v68, v190, 0x41000000, v60
	v_fmamk_f32 v72, v190, 0x41800000, v60
	v_fmamk_f32 v76, v190, 0x41c00000, v60
	v_fmamk_f32 v48, v190, 0x42000000, v60
	v_fmamk_f32 v52, v190, 0x42200000, v60
	v_fmamk_f32 v56, v190, 0x42400000, v60
	v_fmac_f32_e32 v60, 0x42600000, v190
	v_pk_add_f32 v[66:67], v[252:253], v[64:65] op_sel_hi:[1,0]
	v_pk_add_f32 v[64:65], v[224:225], v[64:65] op_sel_hi:[1,0]
	v_pk_add_f32 v[70:71], v[252:253], v[68:69] op_sel_hi:[1,0]
	v_pk_add_f32 v[68:69], v[224:225], v[68:69] op_sel_hi:[1,0]
	v_pk_add_f32 v[74:75], v[252:253], v[72:73] op_sel_hi:[1,0]
	v_pk_add_f32 v[72:73], v[224:225], v[72:73] op_sel_hi:[1,0]
	v_pk_add_f32 v[78:79], v[252:253], v[76:77] op_sel_hi:[1,0]
	v_pk_add_f32 v[76:77], v[224:225], v[76:77] op_sel_hi:[1,0]
	v_pk_add_f32 v[50:51], v[252:253], v[48:49] op_sel_hi:[1,0]
	v_pk_add_f32 v[48:49], v[224:225], v[48:49] op_sel_hi:[1,0]
	v_pk_add_f32 v[54:55], v[252:253], v[52:53] op_sel_hi:[1,0]
	v_pk_add_f32 v[52:53], v[224:225], v[52:53] op_sel_hi:[1,0]
	v_pk_add_f32 v[58:59], v[252:253], v[56:57] op_sel_hi:[1,0]
	v_pk_add_f32 v[56:57], v[224:225], v[56:57] op_sel_hi:[1,0]
	v_pk_add_f32 v[62:63], v[252:253], v[60:61] op_sel_hi:[1,0]
	v_pk_add_f32 v[60:61], v[224:225], v[60:61] op_sel_hi:[1,0]
	s_cbranch_scc1 .Lm01_qk
	v_sub_f32_e32 v254, v189, v1
	v_cmp_lt_f32_e32 vcc, v64, v254
	s_nop 1
	v_cndmask_b32_e32 v64, v241, v64, vcc
	v_cmp_lt_f32_e32 vcc, v65, v254
	s_nop 1
	v_cndmask_b32_e32 v65, v241, v65, vcc
	v_cmp_lt_f32_e32 vcc, v66, v254
	s_nop 1
	v_cndmask_b32_e32 v66, v241, v66, vcc
	v_cmp_lt_f32_e32 vcc, v67, v254
	s_nop 1
	v_cndmask_b32_e32 v67, v241, v67, vcc
	v_cmp_lt_f32_e32 vcc, v68, v254
	s_nop 1
	v_cndmask_b32_e32 v68, v241, v68, vcc
	v_cmp_lt_f32_e32 vcc, v69, v254
	s_nop 1
	v_cndmask_b32_e32 v69, v241, v69, vcc
	v_cmp_lt_f32_e32 vcc, v70, v254
	s_nop 1
	v_cndmask_b32_e32 v70, v241, v70, vcc
	v_cmp_lt_f32_e32 vcc, v71, v254
	s_nop 1
	v_cndmask_b32_e32 v71, v241, v71, vcc
	v_cmp_lt_f32_e32 vcc, v72, v254
	s_nop 1
	v_cndmask_b32_e32 v72, v241, v72, vcc
	v_cmp_lt_f32_e32 vcc, v73, v254
	s_nop 1
	v_cndmask_b32_e32 v73, v241, v73, vcc
	v_cmp_lt_f32_e32 vcc, v74, v254
	s_nop 1
	v_cndmask_b32_e32 v74, v241, v74, vcc
	v_cmp_lt_f32_e32 vcc, v75, v254
	s_nop 1
	v_cndmask_b32_e32 v75, v241, v75, vcc
	v_cmp_lt_f32_e32 vcc, v76, v254
	s_nop 1
	v_cndmask_b32_e32 v76, v241, v76, vcc
	v_cmp_lt_f32_e32 vcc, v77, v254
	s_nop 1
	v_cndmask_b32_e32 v77, v241, v77, vcc
	v_cmp_lt_f32_e32 vcc, v78, v254
	s_nop 1
	v_cndmask_b32_e32 v78, v241, v78, vcc
	v_cmp_lt_f32_e32 vcc, v79, v254
	s_nop 1
	v_cndmask_b32_e32 v79, v241, v79, vcc
	v_cmp_lt_f32_e32 vcc, v48, v254
	s_nop 1
	v_cndmask_b32_e32 v48, v241, v48, vcc
	v_cmp_lt_f32_e32 vcc, v49, v254
	s_nop 1
	v_cndmask_b32_e32 v49, v241, v49, vcc
	v_cmp_lt_f32_e32 vcc, v50, v254
	s_nop 1
	v_cndmask_b32_e32 v50, v241, v50, vcc
	v_cmp_lt_f32_e32 vcc, v51, v254
	s_nop 1
	v_cndmask_b32_e32 v51, v241, v51, vcc
	v_cmp_lt_f32_e32 vcc, v52, v254
	s_nop 1
	v_cndmask_b32_e32 v52, v241, v52, vcc
	v_cmp_lt_f32_e32 vcc, v53, v254
	s_nop 1
	v_cndmask_b32_e32 v53, v241, v53, vcc
	v_cmp_lt_f32_e32 vcc, v54, v254
	s_nop 1
	v_cndmask_b32_e32 v54, v241, v54, vcc
	v_cmp_lt_f32_e32 vcc, v55, v254
	s_nop 1
	v_cndmask_b32_e32 v55, v241, v55, vcc
	v_cmp_lt_f32_e32 vcc, v56, v254
	s_nop 1
	v_cndmask_b32_e32 v56, v241, v56, vcc
	v_cmp_lt_f32_e32 vcc, v57, v254
	s_nop 1
	v_cndmask_b32_e32 v57, v241, v57, vcc
	v_cmp_lt_f32_e32 vcc, v58, v254
	s_nop 1
	v_cndmask_b32_e32 v58, v241, v58, vcc
	v_cmp_lt_f32_e32 vcc, v59, v254
	s_nop 1
	v_cndmask_b32_e32 v59, v241, v59, vcc
	v_cmp_lt_f32_e32 vcc, v60, v254
	s_nop 1
	v_cndmask_b32_e32 v60, v241, v60, vcc
	v_cmp_lt_f32_e32 vcc, v61, v254
	s_nop 1
	v_cndmask_b32_e32 v61, v241, v61, vcc
	v_cmp_lt_f32_e32 vcc, v62, v254
	s_nop 1
	v_cndmask_b32_e32 v62, v241, v62, vcc
	v_cmp_lt_f32_e32 vcc, v63, v254
	s_nop 1
	v_cndmask_b32_e32 v63, v241, v63, vcc

; #define LAS __attribute__((address_space(3)))
; template <int MODE  > ...
;     ...
;     {
;         LAS bf16_t* kb = (LAS bf16_t*)(lds + A_KBUF) + cur * 64 * KPITCH;
;         *(LAS u32x4*)(kb + skey * KPITCH + schunk * 8) = kreg;
;         if (NEEDV) { LAS bf16_t* vb = (LAS bf16_t*)(lds + A_VBUF) + cur * 64 * VPITCH;
;             *(LAS u32x4*)(vb + skey * VPITCH + schunk * 8) = vreg; }
;     }
;     __syncthreads();
;     for (;;) {
;         const bool has_next = rem != 0ull; int jn = 0;
;         if (has_next) { jn = 63 - __builtin_clzll(rem); rem &= ~(1ull << jn);
;             kreg = *(const u32x4*)(Kg + (size_t)(64 * jn + skey) * 128 + schunk * 8);
;             if (NEEDV) vreg = *(const u32x4*)(Vg + (size_t)(64 * jn + skey) * 128 + schunk * 8); }
.Lm1_pre_w:
	s_waitcnt lgkmcnt(0)
	ds_write_b128 v166, v[220:223]
	ds_write_b128 v167, v[248:251] offset:18432
	s_waitcnt lgkmcnt(0)
	s_barrier
	s_lshl_b32 s4, s22, 1
	s_add_u32 s14, s49, s4
	s_addc_u32 s15, s82, 0
	s_add_u32 s4, s47, s4
	s_addc_u32 s5, s48, 0
	v_lshl_add_u32 v2, s83, 6, v164
	v_ashrrev_i32_e32 v3, 31, v2
	v_lshlrev_b64 v[2:3], 8, v[2:3]
	v_lshlrev_b32_e32 v4, 4, v178
	v_and_b32_e32 v4, 0x70, v4
	v_or_b32_e32 v2, v2, v4
	v_lshl_add_u64 v[4:5], s[14:15], 0, v[2:3]
	global_load_dwordx4 v[220:223], v[4:5], off
	v_lshl_add_u64 v[4:5], s[4:5], 0, v[2:3]
	global_load_dwordx4 v[248:251], v[4:5], off
	v_mov_b32_e32 v224, 0
	v_mov_b32_e32 v225, v186
	v_mov_b32_e32 v252, v187
	v_mov_b32_e32 v253, v163

; #define LAS __attribute__((address_space(3)))
; template <int MODE  > ...
;     ...
;         const bool selbit = (MODE == 1) ? (((selmask >> j) & 1ull) != 0ull) : true;
;         bool active = true;
;         if (MODE == 1) active = __builtin_amdgcn_ballot_w64(selbit) != 0ull;
;         if (active) {
;             const LAS bf16_t* kb = (const LAS bf16_t*)(lds + A_KBUF) + cur * 64 * KPITCH;
;             constexpr int STEP = CMPM ? 16 : 1;
;             const int Bint = CMPM ? (1024 * j + 31 - t + 64 * h) : (64 * j - t + 4 * h);
;             const float sl = slope2 * (float)STEP;
;             const float mref = st.m; const bool fresh = !(mref > -1e28f);
;             const float mest = fresh ? 0.f : mref;
;             const float basef = selbit ? (slope2 * (float)Bint - mest) : -1e30f;
;             int ptype;
;             if (MODE == 1) ptype = (j == cblk) ? 1 : 0;
;             else if (MODE == 2) ptype = (j == cblk) ? 1 : ((j == cblk - 8) ? 2 : 0);
;             else ptype = (64 * j + 63 <= 4 * cblk - 2) ? 0 : 1;
;             f32x16 s0, s1;
;             { const float sl2 = sl + sl, sl3 = sl2 + sl;
; #pragma unroll
;               for (int g8 = 0; g8 < 4; ++g8) {
;                   const float b0 = __builtin_fmaf(sl, (float)(8 * g8), basef), b1 = __builtin_fmaf(sl, (float)(8 * g8 + 32), basef);
;                   s0[4 * g8] = b0; s0[4 * g8 + 1] = b0 + sl; s0[4 * g8 + 2] = b0 + sl2; s0[4 * g8 + 3] = b0 + sl3;
;                   s1[4 * g8] = b1; s1[4 * g8 + 1] = b1 + sl; s1[4 * g8 + 2] = b1 + sl2; s1[4 * g8 + 3] = b1 + sl3;
;               } }
;             if (ptype == 1) {
;                 const float thr = 0.5f * slope2 - mest;
; #pragma unroll
;                 for (int i = 0; i < 16; ++i) { s0[i] = (s0[i] < thr) ? s0[i] : -1e30f; s1[i] = (s1[i] < thr) ? s1[i] : -1e30f; }
;             } else if (ptype == 2) {
;                 const float thr = -511.5f * slope2 - mest;
; #pragma unroll
;                 for (int i = 0; i < 16; ++i) { s0[i] = (s0[i] > thr) ? s0[i] : -1e30f; s1[i] = (s1[i] > thr) ? s1[i] : -1e30f; }
;             }
; #pragma unroll
;             for (int kk = 0; kk < 4; ++kk) {
;                 const bf16x8 k0 = *(const LAS bf16x8*)(kb + col * KPITCH + kk * 16 + h * 8);
;                 const bf16x8 k1 = *(const LAS bf16x8*)(kb + (32 + col) * KPITCH + kk * 16 + h * 8);
.Lm10_noload:
.Lm1_body0:
	v_lshrrev_b64 v[2:3], s68, v[140:141]
	v_and_b32_e32 v1, 1, v2
	v_cmp_eq_u32_e64 s[16:17], 1, v1
	v_cmp_ne_u32_e32 vcc, 0, v1
	s_cbranch_vccz .Lm1_stage0
	ds_read_b128 v[66:69], v191
	ds_read_b128 v[70:73], v191 offset:4608
	ds_read_b128 v[74:77], v191 offset:32
	ds_read_b128 v[78:81], v191 offset:4640
	ds_read_b128 v[82:85], v191 offset:64
	ds_read_b128 v[86:89], v191 offset:4672
	ds_read_b128 v[90:93], v191 offset:96
	ds_read_b128 v[94:97], v191 offset:4704
	v_lshl_add_u32 v1, s68, 6, v190
	v_cvt_f32_i32_e32 v2, v1
	v_cmp_nlt_f32_e64 s[14:15], s71, v194
	s_cmp_lg_u32 s68, s83
	s_nop 0
	v_cndmask_b32_e64 v1, v194, 0, s[14:15]
	v_fma_f32 v2, v186, v2, -v1
	v_cndmask_b32_e64 v14, v241, v2, s[16:17]
	v_fma_f32 v50, 0, v186, v14
	v_fmamk_f32 v54, v186, 0x41000000, v14
	v_fmamk_f32 v58, v186, 0x41800000, v14
	v_fmamk_f32 v62, v186, 0x41c00000, v14
	v_fmamk_f32 v2, v186, 0x42000000, v14
	v_fmamk_f32 v6, v186, 0x42200000, v14
	v_fmamk_f32 v10, v186, 0x42400000, v14
	v_fmac_f32_e32 v14, 0x42600000, v186
	v_pk_add_f32 v[52:53], v[252:253], v[50:51] op_sel_hi:[1,0]
	v_pk_add_f32 v[50:51], v[224:225], v[50:51] op_sel_hi:[1,0]
	v_pk_add_f32 v[56:57], v[252:253], v[54:55] op_sel_hi:[1,0]
	v_pk_add_f32 v[54:55], v[224:225], v[54:55] op_sel_hi:[1,0]
	v_pk_add_f32 v[60:61], v[252:253], v[58:59] op_sel_hi:[1,0]
	v_pk_add_f32 v[58:59], v[224:225], v[58:59] op_sel_hi:[1,0]
	v_pk_add_f32 v[64:65], v[252:253], v[62:63] op_sel_hi:[1,0]
	v_pk_add_f32 v[62:63], v[224:225], v[62:63] op_sel_hi:[1,0]
	v_pk_add_f32 v[4:5], v[252:253], v[2:3] op_sel_hi:[1,0]
	v_pk_add_f32 v[2:3], v[224:225], v[2:3] op_sel_hi:[1,0]
	v_pk_add_f32 v[8:9], v[252:253], v[6:7] op_sel_hi:[1,0]
	v_pk_add_f32 v[6:7], v[224:225], v[6:7] op_sel_hi:[1,0]
	v_pk_add_f32 v[12:13], v[252:253], v[10:11] op_sel_hi:[1,0]
	v_pk_add_f32 v[10:11], v[224:225], v[10:11] op_sel_hi:[1,0]
	v_pk_add_f32 v[16:17], v[252:253], v[14:15] op_sel_hi:[1,0]
	v_pk_add_f32 v[14:15], v[224:225], v[14:15] op_sel_hi:[1,0]
	s_cbranch_scc1 .Lm10_qk
	v_sub_f32_e32 v254, v189, v1
	v_cmp_lt_f32_e32 vcc, v50, v254
	s_nop 1
	v_cndmask_b32_e32 v50, v241, v50, vcc
	v_cmp_lt_f32_e32 vcc, v51, v254
	s_nop 1
	v_cndmask_b32_e32 v51, v241, v51, vcc
	v_cmp_lt_f32_e32 vcc, v52, v254
	s_nop 1
	v_cndmask_b32_e32 v52, v241, v52, vcc
	v_cmp_lt_f32_e32 vcc, v53, v254
	s_nop 1
	v_cndmask_b32_e32 v53, v241, v53, vcc
	v_cmp_lt_f32_e32 vcc, v54, v254
	s_nop 1
	v_cndmask_b32_e32 v54, v241, v54, vcc
	v_cmp_lt_f32_e32 vcc, v55, v254
	s_nop 1
	v_cndmask_b32_e32 v55, v241, v55, vcc
	v_cmp_lt_f32_e32 vcc, v56, v254
	s_nop 1
	v_cndmask_b32_e32 v56, v241, v56, vcc
	v_cmp_lt_f32_e32 vcc, v57, v254
	s_nop 1
	v_cndmask_b32_e32 v57, v241, v57, vcc
	v_cmp_lt_f32_e32 vcc, v58, v254
	s_nop 1
	v_cndmask_b32_e32 v58, v241, v58, vcc
	v_cmp_lt_f32_e32 vcc, v59, v254
	s_nop 1
	v_cndmask_b32_e32 v59, v241, v59, vcc
	v_cmp_lt_f32_e32 vcc, v60, v254
	s_nop 1
	v_cndmask_b32_e32 v60, v241, v60, vcc
	v_cmp_lt_f32_e32 vcc, v61, v254
	s_nop 1
	v_cndmask_b32_e32 v61, v241, v61, vcc
	v_cmp_lt_f32_e32 vcc, v62, v254
	s_nop 1
	v_cndmask_b32_e32 v62, v241, v62, vcc
	v_cmp_lt_f32_e32 vcc, v63, v254
	s_nop 1
	v_cndmask_b32_e32 v63, v241, v63, vcc
	v_cmp_lt_f32_e32 vcc, v64, v254
	s_nop 1
	v_cndmask_b32_e32 v64, v241, v64, vcc
	v_cmp_lt_f32_e32 vcc, v65, v254
	s_nop 1
	v_cndmask_b32_e32 v65, v241, v65, vcc
	v_cmp_lt_f32_e32 vcc, v2, v254
	s_nop 1
	v_cndmask_b32_e32 v2, v241, v2, vcc
	v_cmp_lt_f32_e32 vcc, v3, v254
	s_nop 1
	v_cndmask_b32_e32 v3, v241, v3, vcc
	v_cmp_lt_f32_e32 vcc, v4, v254
	s_nop 1
	v_cndmask_b32_e32 v4, v241, v4, vcc
	v_cmp_lt_f32_e32 vcc, v5, v254
	s_nop 1
	v_cndmask_b32_e32 v5, v241, v5, vcc
	v_cmp_lt_f32_e32 vcc, v6, v254
	s_nop 1
	v_cndmask_b32_e32 v6, v241, v6, vcc
	v_cmp_lt_f32_e32 vcc, v7, v254
	s_nop 1
	v_cndmask_b32_e32 v7, v241, v7, vcc
	v_cmp_lt_f32_e32 vcc, v8, v254
	s_nop 1
	v_cndmask_b32_e32 v8, v241, v8, vcc
	v_cmp_lt_f32_e32 vcc, v9, v254
	s_nop 1
	v_cndmask_b32_e32 v9, v241, v9, vcc
	v_cmp_lt_f32_e32 vcc, v10, v254
	s_nop 1
	v_cndmask_b32_e32 v10, v241, v10, vcc
	v_cmp_lt_f32_e32 vcc, v11, v254
	s_nop 1
	v_cndmask_b32_e32 v11, v241, v11, vcc
	v_cmp_lt_f32_e32 vcc, v12, v254
	s_nop 1
	v_cndmask_b32_e32 v12, v241, v12, vcc
	v_cmp_lt_f32_e32 vcc, v13, v254
	s_nop 1
	v_cndmask_b32_e32 v13, v241, v13, vcc
	v_cmp_lt_f32_e32 vcc, v14, v254
	s_nop 1
	v_cndmask_b32_e32 v14, v241, v14, vcc
	v_cmp_lt_f32_e32 vcc, v15, v254
	s_nop 1
	v_cndmask_b32_e32 v15, v241, v15, vcc
	v_cmp_lt_f32_e32 vcc, v16, v254
	s_nop 1
	v_cndmask_b32_e32 v16, v241, v16, vcc
	v_cmp_lt_f32_e32 vcc, v17, v254
	s_nop 1
	v_cndmask_b32_e32 v17, v241, v17, vcc

; #define LAS __attribute__((address_space(3)))
; template <int MODE  > ...
;     ...
;         const bool selbit = (MODE == 1) ? (((selmask >> j) & 1ull) != 0ull) : true;
;         bool active = true;
;         if (MODE == 1) active = __builtin_amdgcn_ballot_w64(selbit) != 0ull;
;         if (active) {
;             const LAS bf16_t* kb = (const LAS bf16_t*)(lds + A_KBUF) + cur * 64 * KPITCH;
;             constexpr int STEP = CMPM ? 16 : 1;
;             const int Bint = CMPM ? (1024 * j + 31 - t + 64 * h) : (64 * j - t + 4 * h);
;             const float sl = slope2 * (float)STEP;
;             const float mref = st.m; const bool fresh = !(mref > -1e28f);
;             const float mest = fresh ? 0.f : mref;
;             const float basef = selbit ? (slope2 * (float)Bint - mest) : -1e30f;
;             int ptype;
;             if (MODE == 1) ptype = (j == cblk) ? 1 : 0;
;             else if (MODE == 2) ptype = (j == cblk) ? 1 : ((j == cblk - 8) ? 2 : 0);
;             else ptype = (64 * j + 63 <= 4 * cblk - 2) ? 0 : 1;
;             f32x16 s0, s1;
;             { const float sl2 = sl + sl, sl3 = sl2 + sl;
; #pragma unroll
;               for (int g8 = 0; g8 < 4; ++g8) {
;                   const float b0 = __builtin_fmaf(sl, (float)(8 * g8), basef), b1 = __builtin_fmaf(sl, (float)(8 * g8 + 32), basef);
;                   s0[4 * g8] = b0; s0[4 * g8 + 1] = b0 + sl; s0[4 * g8 + 2] = b0 + sl2; s0[4 * g8 + 3] = b0 + sl3;
;                   s1[4 * g8] = b1; s1[4 * g8 + 1] = b1 + sl; s1[4 * g8 + 2] = b1 + sl2; s1[4 * g8 + 3] = b1 + sl3;
;               } }
;             if (ptype == 1) {
;                 const float thr = 0.5f * slope2 - mest;
; #pragma unroll
;                 for (int i = 0; i < 16; ++i) { s0[i] = (s0[i] < thr) ? s0[i] : -1e30f; s1[i] = (s1[i] < thr) ? s1[i] : -1e30f; }
;             } else if (ptype == 2) {
;                 const float thr = -511.5f * slope2 - mest;
; #pragma unroll
;                 for (int i = 0; i < 16; ++i) { s0[i] = (s0[i] > thr) ? s0[i] : -1e30f; s1[i] = (s1[i] > thr) ? s1[i] : -1e30f; }
;             }
; #pragma unroll
;             for (int kk = 0; kk < 4; ++kk) {
;                 const bf16x8 k0 = *(const LAS bf16x8*)(kb + col * KPITCH + kk * 16 + h * 8);
;                 const bf16x8 k1 = *(const LAS bf16x8*)(kb + (32 + col) * KPITCH + kk * 16 + h * 8);
.Lm11_noload:
.Lm1_body1:
	v_lshrrev_b64 v[2:3], s68, v[140:141]
	v_and_b32_e32 v1, 1, v2
	v_cmp_eq_u32_e64 s[16:17], 1, v1
	v_cmp_ne_u32_e32 vcc, 0, v1
	s_cbranch_vccz .Lm1_stage1
	ds_read_b128 v[66:69], v191 offset:9216
	ds_read_b128 v[70:73], v191 offset:13824
	ds_read_b128 v[74:77], v191 offset:9248
	ds_read_b128 v[78:81], v191 offset:13856
	ds_read_b128 v[82:85], v191 offset:9280
	ds_read_b128 v[86:89], v191 offset:13888
	ds_read_b128 v[90:93], v191 offset:9312
	ds_read_b128 v[94:97], v191 offset:13920
	v_lshl_add_u32 v1, s68, 6, v190
	v_cvt_f32_i32_e32 v2, v1
	v_cmp_nlt_f32_e64 s[14:15], s71, v194
	s_cmp_lg_u32 s68, s83
	s_nop 0
	v_cndmask_b32_e64 v1, v194, 0, s[14:15]
	v_fma_f32 v2, v186, v2, -v1
	v_cndmask_b32_e64 v14, v241, v2, s[16:17]
	v_fma_f32 v50, 0, v186, v14
	v_fmamk_f32 v54, v186, 0x41000000, v14
	v_fmamk_f32 v58, v186, 0x41800000, v14
	v_fmamk_f32 v62, v186, 0x41c00000, v14
	v_fmamk_f32 v2, v186, 0x42000000, v14
	v_fmamk_f32 v6, v186, 0x42200000, v14
	v_fmamk_f32 v10, v186, 0x42400000, v14
	v_fmac_f32_e32 v14, 0x42600000, v186
	v_pk_add_f32 v[52:53], v[252:253], v[50:51] op_sel_hi:[1,0]
	v_pk_add_f32 v[50:51], v[224:225], v[50:51] op_sel_hi:[1,0]
	v_pk_add_f32 v[56:57], v[252:253], v[54:55] op_sel_hi:[1,0]
	v_pk_add_f32 v[54:55], v[224:225], v[54:55] op_sel_hi:[1,0]
	v_pk_add_f32 v[60:61], v[252:253], v[58:59] op_sel_hi:[1,0]
	v_pk_add_f32 v[58:59], v[224:225], v[58:59] op_sel_hi:[1,0]
	v_pk_add_f32 v[64:65], v[252:253], v[62:63] op_sel_hi:[1,0]
	v_pk_add_f32 v[62:63], v[224:225], v[62:63] op_sel_hi:[1,0]
	v_pk_add_f32 v[4:5], v[252:253], v[2:3] op_sel_hi:[1,0]
	v_pk_add_f32 v[2:3], v[224:225], v[2:3] op_sel_hi:[1,0]
	v_pk_add_f32 v[8:9], v[252:253], v[6:7] op_sel_hi:[1,0]
	v_pk_add_f32 v[6:7], v[224:225], v[6:7] op_sel_hi:[1,0]
	v_pk_add_f32 v[12:13], v[252:253], v[10:11] op_sel_hi:[1,0]
	v_pk_add_f32 v[10:11], v[224:225], v[10:11] op_sel_hi:[1,0]
	v_pk_add_f32 v[16:17], v[252:253], v[14:15] op_sel_hi:[1,0]
	v_pk_add_f32 v[14:15], v[224:225], v[14:15] op_sel_hi:[1,0]
	s_cbranch_scc1 .Lm11_qk
	v_sub_f32_e32 v254, v189, v1
	v_cmp_lt_f32_e32 vcc, v50, v254
	s_nop 1
	v_cndmask_b32_e32 v50, v241, v50, vcc
	v_cmp_lt_f32_e32 vcc, v51, v254
	s_nop 1
	v_cndmask_b32_e32 v51, v241, v51, vcc
	v_cmp_lt_f32_e32 vcc, v52, v254
	s_nop 1
	v_cndmask_b32_e32 v52, v241, v52, vcc
	v_cmp_lt_f32_e32 vcc, v53, v254
	s_nop 1
	v_cndmask_b32_e32 v53, v241, v53, vcc
	v_cmp_lt_f32_e32 vcc, v54, v254
	s_nop 1
	v_cndmask_b32_e32 v54, v241, v54, vcc
	v_cmp_lt_f32_e32 vcc, v55, v254
	s_nop 1
	v_cndmask_b32_e32 v55, v241, v55, vcc
	v_cmp_lt_f32_e32 vcc, v56, v254
	s_nop 1
	v_cndmask_b32_e32 v56, v241, v56, vcc
	v_cmp_lt_f32_e32 vcc, v57, v254
	s_nop 1
	v_cndmask_b32_e32 v57, v241, v57, vcc
	v_cmp_lt_f32_e32 vcc, v58, v254
	s_nop 1
	v_cndmask_b32_e32 v58, v241, v58, vcc
	v_cmp_lt_f32_e32 vcc, v59, v254
	s_nop 1
	v_cndmask_b32_e32 v59, v241, v59, vcc
	v_cmp_lt_f32_e32 vcc, v60, v254
	s_nop 1
	v_cndmask_b32_e32 v60, v241, v60, vcc
	v_cmp_lt_f32_e32 vcc, v61, v254
	s_nop 1
	v_cndmask_b32_e32 v61, v241, v61, vcc
	v_cmp_lt_f32_e32 vcc, v62, v254
	s_nop 1
	v_cndmask_b32_e32 v62, v241, v62, vcc
	v_cmp_lt_f32_e32 vcc, v63, v254
	s_nop 1
	v_cndmask_b32_e32 v63, v241, v63, vcc
	v_cmp_lt_f32_e32 vcc, v64, v254
	s_nop 1
	v_cndmask_b32_e32 v64, v241, v64, vcc
	v_cmp_lt_f32_e32 vcc, v65, v254
	s_nop 1
	v_cndmask_b32_e32 v65, v241, v65, vcc
	v_cmp_lt_f32_e32 vcc, v2, v254
	s_nop 1
	v_cndmask_b32_e32 v2, v241, v2, vcc
	v_cmp_lt_f32_e32 vcc, v3, v254
	s_nop 1
	v_cndmask_b32_e32 v3, v241, v3, vcc
	v_cmp_lt_f32_e32 vcc, v4, v254
	s_nop 1
	v_cndmask_b32_e32 v4, v241, v4, vcc
	v_cmp_lt_f32_e32 vcc, v5, v254
	s_nop 1
	v_cndmask_b32_e32 v5, v241, v5, vcc
	v_cmp_lt_f32_e32 vcc, v6, v254
	s_nop 1
	v_cndmask_b32_e32 v6, v241, v6, vcc
	v_cmp_lt_f32_e32 vcc, v7, v254
	s_nop 1
	v_cndmask_b32_e32 v7, v241, v7, vcc
	v_cmp_lt_f32_e32 vcc, v8, v254
	s_nop 1
	v_cndmask_b32_e32 v8, v241, v8, vcc
	v_cmp_lt_f32_e32 vcc, v9, v254
	s_nop 1
	v_cndmask_b32_e32 v9, v241, v9, vcc
	v_cmp_lt_f32_e32 vcc, v10, v254
	s_nop 1
	v_cndmask_b32_e32 v10, v241, v10, vcc
	v_cmp_lt_f32_e32 vcc, v11, v254
	s_nop 1
	v_cndmask_b32_e32 v11, v241, v11, vcc
	v_cmp_lt_f32_e32 vcc, v12, v254
	s_nop 1
	v_cndmask_b32_e32 v12, v241, v12, vcc
	v_cmp_lt_f32_e32 vcc, v13, v254
	s_nop 1
	v_cndmask_b32_e32 v13, v241, v13, vcc
	v_cmp_lt_f32_e32 vcc, v14, v254
	s_nop 1
	v_cndmask_b32_e32 v14, v241, v14, vcc
	v_cmp_lt_f32_e32 vcc, v15, v254
	s_nop 1
	v_cndmask_b32_e32 v15, v241, v15, vcc
	v_cmp_lt_f32_e32 vcc, v16, v254
	s_nop 1
	v_cndmask_b32_e32 v16, v241, v16, vcc
	v_cmp_lt_f32_e32 vcc, v17, v254
	s_nop 1
	v_cndmask_b32_e32 v17, v241, v17, vcc

; #define LAS __attribute__((address_space(3)))
; template <int MODE  > ...
;     ...
;     {
;         LAS bf16_t* kb = (LAS bf16_t*)(lds + A_KBUF) + cur * 64 * KPITCH;
;         *(LAS u32x4*)(kb + skey * KPITCH + schunk * 8) = kreg;
;         if (NEEDV) { LAS bf16_t* vb = (LAS bf16_t*)(lds + A_VBUF) + cur * 64 * VPITCH;
;             *(LAS u32x4*)(vb + skey * VPITCH + schunk * 8) = vreg; }
;     }
;     __syncthreads();
.Lm2_pre_w:
	s_waitcnt lgkmcnt(0)
	ds_write_b128 v165, v[220:223]
	ds_write_b128 v166, v[248:251] offset:18432
	s_waitcnt lgkmcnt(0)
	s_barrier
	v_mov_b32_e32 v224, 0
	v_mov_b32_e32 v225, v186
	v_mov_b32_e32 v252, v187
	v_mov_b32_e32 v253, v163

; #define LAS __attribute__((address_space(3)))
; template <int MODE  > ...
;     ...
;             const LAS bf16_t* kb = (const LAS bf16_t*)(lds + A_KBUF) + cur * 64 * KPITCH;
;             constexpr int STEP = CMPM ? 16 : 1;
;             const int Bint = CMPM ? (1024 * j + 31 - t + 64 * h) : (64 * j - t + 4 * h);
;             const float sl = slope2 * (float)STEP;
;             const float mref = st.m; const bool fresh = !(mref > -1e28f);
;             const float mest = fresh ? 0.f : mref;
;             const float basef = selbit ? (slope2 * (float)Bint - mest) : -1e30f;
;             int ptype;
;             if (MODE == 1) ptype = (j == cblk) ? 1 : 0;
;             else if (MODE == 2) ptype = (j == cblk) ? 1 : ((j == cblk - 8) ? 2 : 0);
;             else ptype = (64 * j + 63 <= 4 * cblk - 2) ? 0 : 1;
;             f32x16 s0, s1;
;             { const float sl2 = sl + sl, sl3 = sl2 + sl;
; #pragma unroll
;               for (int g8 = 0; g8 < 4; ++g8) {
;                   const float b0 = __builtin_fmaf(sl, (float)(8 * g8), basef), b1 = __builtin_fmaf(sl, (float)(8 * g8 + 32), basef);
;                   s0[4 * g8] = b0; s0[4 * g8 + 1] = b0 + sl; s0[4 * g8 + 2] = b0 + sl2; s0[4 * g8 + 3] = b0 + sl3;
;                   s1[4 * g8] = b1; s1[4 * g8 + 1] = b1 + sl; s1[4 * g8 + 2] = b1 + sl2; s1[4 * g8 + 3] = b1 + sl3;
;               } }
;             if (ptype == 1) {
;                 const float thr = 0.5f * slope2 - mest;
; #pragma unroll
;                 for (int i = 0; i < 16; ++i) { s0[i] = (s0[i] < thr) ? s0[i] : -1e30f; s1[i] = (s1[i] < thr) ? s1[i] : -1e30f; }
;             } else if (ptype == 2) {
;                 const float thr = -511.5f * slope2 - mest;
; #pragma unroll
;                 for (int i = 0; i < 16; ++i) { s0[i] = (s0[i] > thr) ? s0[i] : -1e30f; s1[i] = (s1[i] > thr) ? s1[i] : -1e30f; }
;             }
.Lm20_noload:
.Lm2_body0:
	ds_read_b128 v[66:69], v188
	ds_read_b128 v[70:73], v188 offset:4608
	ds_read_b128 v[74:77], v188 offset:32
	ds_read_b128 v[78:81], v188 offset:4640
	ds_read_b128 v[82:85], v188 offset:64
	ds_read_b128 v[86:89], v188 offset:4672
	ds_read_b128 v[90:93], v188 offset:96
	ds_read_b128 v[94:97], v188 offset:4704
	v_lshl_add_u32 v1, s20, 6, v167
	v_cvt_f32_i32_e32 v50, v1
	v_cmp_nlt_f32_e64 s[14:15], s71, v192
	s_cmp_eq_u32 s20, s23
	s_cselect_b32 s21, 2, 0
	s_cmp_lg_u32 s20, s83
	s_cselect_b32 s68, s21, 1
	s_cmp_eq_u32 s68, 0
	v_cndmask_b32_e64 v1, v192, 0, s[14:15]
	v_fma_f32 v62, v186, v50, -v1
	v_fma_f32 v34, 0, v186, v62
	v_fmamk_f32 v38, v186, 0x41000000, v62
	v_fmamk_f32 v42, v186, 0x41800000, v62
	v_fmamk_f32 v46, v186, 0x41c00000, v62
	v_fmamk_f32 v50, v186, 0x42000000, v62
	v_fmamk_f32 v54, v186, 0x42200000, v62
	v_fmamk_f32 v58, v186, 0x42400000, v62
	v_fmac_f32_e32 v62, 0x42600000, v186
	v_pk_add_f32 v[36:37], v[252:253], v[34:35] op_sel_hi:[1,0]
	v_pk_add_f32 v[34:35], v[224:225], v[34:35] op_sel_hi:[1,0]
	v_pk_add_f32 v[40:41], v[252:253], v[38:39] op_sel_hi:[1,0]
	v_pk_add_f32 v[38:39], v[224:225], v[38:39] op_sel_hi:[1,0]
	v_pk_add_f32 v[44:45], v[252:253], v[42:43] op_sel_hi:[1,0]
	v_pk_add_f32 v[42:43], v[224:225], v[42:43] op_sel_hi:[1,0]
	v_pk_add_f32 v[48:49], v[252:253], v[46:47] op_sel_hi:[1,0]
	v_pk_add_f32 v[46:47], v[224:225], v[46:47] op_sel_hi:[1,0]
	v_pk_add_f32 v[52:53], v[252:253], v[50:51] op_sel_hi:[1,0]
	v_pk_add_f32 v[50:51], v[224:225], v[50:51] op_sel_hi:[1,0]
	v_pk_add_f32 v[56:57], v[252:253], v[54:55] op_sel_hi:[1,0]
	v_pk_add_f32 v[54:55], v[224:225], v[54:55] op_sel_hi:[1,0]
	v_pk_add_f32 v[60:61], v[252:253], v[58:59] op_sel_hi:[1,0]
	v_pk_add_f32 v[58:59], v[224:225], v[58:59] op_sel_hi:[1,0]
	v_pk_add_f32 v[64:65], v[252:253], v[62:63] op_sel_hi:[1,0]
	v_pk_add_f32 v[62:63], v[224:225], v[62:63] op_sel_hi:[1,0]
	s_cbranch_scc1 .Lm20_qk
	s_cmp_eq_u32 s68, 1
	s_cbranch_scc1 .Lm20_edge1
	v_sub_f32_e32 v254, v162, v1
	v_cmp_gt_f32_e32 vcc, v34, v254
	s_nop 1
	v_cndmask_b32_e32 v34, v241, v34, vcc
	v_cmp_gt_f32_e32 vcc, v35, v254
	s_nop 1
	v_cndmask_b32_e32 v35, v241, v35, vcc
	v_cmp_gt_f32_e32 vcc, v36, v254
	s_nop 1
	v_cndmask_b32_e32 v36, v241, v36, vcc
	v_cmp_gt_f32_e32 vcc, v37, v254
	s_nop 1
	v_cndmask_b32_e32 v37, v241, v37, vcc
	v_cmp_gt_f32_e32 vcc, v38, v254
	s_nop 1
	v_cndmask_b32_e32 v38, v241, v38, vcc
	v_cmp_gt_f32_e32 vcc, v39, v254
	s_nop 1
	v_cndmask_b32_e32 v39, v241, v39, vcc
	v_cmp_gt_f32_e32 vcc, v40, v254
	s_nop 1
	v_cndmask_b32_e32 v40, v241, v40, vcc
	v_cmp_gt_f32_e32 vcc, v41, v254
	s_nop 1
	v_cndmask_b32_e32 v41, v241, v41, vcc
	v_cmp_gt_f32_e32 vcc, v42, v254
	s_nop 1
	v_cndmask_b32_e32 v42, v241, v42, vcc
	v_cmp_gt_f32_e32 vcc, v43, v254
	s_nop 1
	v_cndmask_b32_e32 v43, v241, v43, vcc
	v_cmp_gt_f32_e32 vcc, v44, v254
	s_nop 1
	v_cndmask_b32_e32 v44, v241, v44, vcc
	v_cmp_gt_f32_e32 vcc, v45, v254
	s_nop 1
	v_cndmask_b32_e32 v45, v241, v45, vcc
	v_cmp_gt_f32_e32 vcc, v46, v254
	s_nop 1
	v_cndmask_b32_e32 v46, v241, v46, vcc
	v_cmp_gt_f32_e32 vcc, v47, v254
	s_nop 1
	v_cndmask_b32_e32 v47, v241, v47, vcc
	v_cmp_gt_f32_e32 vcc, v48, v254
	s_nop 1
	v_cndmask_b32_e32 v48, v241, v48, vcc
	v_cmp_gt_f32_e32 vcc, v49, v254
	s_nop 1
	v_cndmask_b32_e32 v49, v241, v49, vcc
	v_cmp_gt_f32_e32 vcc, v50, v254
	s_nop 1
	v_cndmask_b32_e32 v50, v241, v50, vcc
	v_cmp_gt_f32_e32 vcc, v51, v254
	s_nop 1
	v_cndmask_b32_e32 v51, v241, v51, vcc
	v_cmp_gt_f32_e32 vcc, v52, v254
	s_nop 1
	v_cndmask_b32_e32 v52, v241, v52, vcc
	v_cmp_gt_f32_e32 vcc, v53, v254
	s_nop 1
	v_cndmask_b32_e32 v53, v241, v53, vcc
	v_cmp_gt_f32_e32 vcc, v54, v254
	s_nop 1
	v_cndmask_b32_e32 v54, v241, v54, vcc
	v_cmp_gt_f32_e32 vcc, v55, v254
	s_nop 1
	v_cndmask_b32_e32 v55, v241, v55, vcc
	v_cmp_gt_f32_e32 vcc, v56, v254
	s_nop 1
	v_cndmask_b32_e32 v56, v241, v56, vcc
	v_cmp_gt_f32_e32 vcc, v57, v254
	s_nop 1
	v_cndmask_b32_e32 v57, v241, v57, vcc
	v_cmp_gt_f32_e32 vcc, v58, v254
	s_nop 1
	v_cndmask_b32_e32 v58, v241, v58, vcc
	v_cmp_gt_f32_e32 vcc, v59, v254
	s_nop 1
	v_cndmask_b32_e32 v59, v241, v59, vcc
	v_cmp_gt_f32_e32 vcc, v60, v254
	s_nop 1
	v_cndmask_b32_e32 v60, v241, v60, vcc
	v_cmp_gt_f32_e32 vcc, v61, v254
	s_nop 1
	v_cndmask_b32_e32 v61, v241, v61, vcc
	v_cmp_gt_f32_e32 vcc, v62, v254
	s_nop 1
	v_cndmask_b32_e32 v62, v241, v62, vcc
	v_cmp_gt_f32_e32 vcc, v63, v254
	s_nop 1
	v_cndmask_b32_e32 v63, v241, v63, vcc
	v_cmp_gt_f32_e32 vcc, v64, v254
	s_nop 1
	v_cndmask_b32_e32 v64, v241, v64, vcc
	v_cmp_gt_f32_e32 vcc, v65, v254
	s_nop 1
	v_cndmask_b32_e32 v65, v241, v65, vcc
	s_branch .Lm20_qk

; #define LAS __attribute__((address_space(3)))
; template <int MODE  > ...
;     ...
;             const LAS bf16_t* kb = (const LAS bf16_t*)(lds + A_KBUF) + cur * 64 * KPITCH;
;             constexpr int STEP = CMPM ? 16 : 1;
;             const int Bint = CMPM ? (1024 * j + 31 - t + 64 * h) : (64 * j - t + 4 * h);
;             const float sl = slope2 * (float)STEP;
;             const float mref = st.m; const bool fresh = !(mref > -1e28f);
;             const float mest = fresh ? 0.f : mref;
;             const float basef = selbit ? (slope2 * (float)Bint - mest) : -1e30f;
;             int ptype;
;             if (MODE == 1) ptype = (j == cblk) ? 1 : 0;
;             else if (MODE == 2) ptype = (j == cblk) ? 1 : ((j == cblk - 8) ? 2 : 0);
;             else ptype = (64 * j + 63 <= 4 * cblk - 2) ? 0 : 1;
;             f32x16 s0, s1;
;             { const float sl2 = sl + sl, sl3 = sl2 + sl;
; #pragma unroll
;               for (int g8 = 0; g8 < 4; ++g8) {
;                   const float b0 = __builtin_fmaf(sl, (float)(8 * g8), basef), b1 = __builtin_fmaf(sl, (float)(8 * g8 + 32), basef);
;                   s0[4 * g8] = b0; s0[4 * g8 + 1] = b0 + sl; s0[4 * g8 + 2] = b0 + sl2; s0[4 * g8 + 3] = b0 + sl3;
;                   s1[4 * g8] = b1; s1[4 * g8 + 1] = b1 + sl; s1[4 * g8 + 2] = b1 + sl2; s1[4 * g8 + 3] = b1 + sl3;
;               } }
;             if (ptype == 1) {
;                 const float thr = 0.5f * slope2 - mest;
; #pragma unroll
;                 for (int i = 0; i < 16; ++i) { s0[i] = (s0[i] < thr) ? s0[i] : -1e30f; s1[i] = (s1[i] < thr) ? s1[i] : -1e30f; }
;             } else if (ptype == 2) {
;                 const float thr = -511.5f * slope2 - mest;
; #pragma unroll
;                 for (int i = 0; i < 16; ++i) { s0[i] = (s0[i] > thr) ? s0[i] : -1e30f; s1[i] = (s1[i] > thr) ? s1[i] : -1e30f; }
;             }
.Lm21_noload:
.Lm2_body1:
	ds_read_b128 v[66:69], v188 offset:9216
	ds_read_b128 v[70:73], v188 offset:13824
	ds_read_b128 v[74:77], v188 offset:9248
	ds_read_b128 v[78:81], v188 offset:13856
	ds_read_b128 v[82:85], v188 offset:9280
	ds_read_b128 v[86:89], v188 offset:13888
	ds_read_b128 v[90:93], v188 offset:9312
	ds_read_b128 v[94:97], v188 offset:13920
	v_lshl_add_u32 v1, s20, 6, v167
	v_cvt_f32_i32_e32 v50, v1
	v_cmp_nlt_f32_e64 s[14:15], s71, v192
	s_cmp_eq_u32 s20, s23
	s_cselect_b32 s21, 2, 0
	s_cmp_lg_u32 s20, s83
	s_cselect_b32 s68, s21, 1
	s_cmp_eq_u32 s68, 0
	v_cndmask_b32_e64 v1, v192, 0, s[14:15]
	v_fma_f32 v62, v186, v50, -v1
	v_fma_f32 v34, 0, v186, v62
	v_fmamk_f32 v38, v186, 0x41000000, v62
	v_fmamk_f32 v42, v186, 0x41800000, v62
	v_fmamk_f32 v46, v186, 0x41c00000, v62
	v_fmamk_f32 v50, v186, 0x42000000, v62
	v_fmamk_f32 v54, v186, 0x42200000, v62
	v_fmamk_f32 v58, v186, 0x42400000, v62
	v_fmac_f32_e32 v62, 0x42600000, v186
	v_pk_add_f32 v[36:37], v[252:253], v[34:35] op_sel_hi:[1,0]
	v_pk_add_f32 v[34:35], v[224:225], v[34:35] op_sel_hi:[1,0]
	v_pk_add_f32 v[40:41], v[252:253], v[38:39] op_sel_hi:[1,0]
	v_pk_add_f32 v[38:39], v[224:225], v[38:39] op_sel_hi:[1,0]
	v_pk_add_f32 v[44:45], v[252:253], v[42:43] op_sel_hi:[1,0]
	v_pk_add_f32 v[42:43], v[224:225], v[42:43] op_sel_hi:[1,0]
	v_pk_add_f32 v[48:49], v[252:253], v[46:47] op_sel_hi:[1,0]
	v_pk_add_f32 v[46:47], v[224:225], v[46:47] op_sel_hi:[1,0]
	v_pk_add_f32 v[52:53], v[252:253], v[50:51] op_sel_hi:[1,0]
	v_pk_add_f32 v[50:51], v[224:225], v[50:51] op_sel_hi:[1,0]
	v_pk_add_f32 v[56:57], v[252:253], v[54:55] op_sel_hi:[1,0]
	v_pk_add_f32 v[54:55], v[224:225], v[54:55] op_sel_hi:[1,0]
	v_pk_add_f32 v[60:61], v[252:253], v[58:59] op_sel_hi:[1,0]
	v_pk_add_f32 v[58:59], v[224:225], v[58:59] op_sel_hi:[1,0]
	v_pk_add_f32 v[64:65], v[252:253], v[62:63] op_sel_hi:[1,0]
	v_pk_add_f32 v[62:63], v[224:225], v[62:63] op_sel_hi:[1,0]
	s_cbranch_scc1 .Lm21_qk
	s_cmp_eq_u32 s68, 1
	s_cbranch_scc1 .Lm21_edge1
	v_sub_f32_e32 v254, v162, v1
	v_cmp_gt_f32_e32 vcc, v34, v254
	s_nop 1
	v_cndmask_b32_e32 v34, v241, v34, vcc
	v_cmp_gt_f32_e32 vcc, v35, v254
	s_nop 1
	v_cndmask_b32_e32 v35, v241, v35, vcc
	v_cmp_gt_f32_e32 vcc, v36, v254
	s_nop 1
	v_cndmask_b32_e32 v36, v241, v36, vcc
	v_cmp_gt_f32_e32 vcc, v37, v254
	s_nop 1
	v_cndmask_b32_e32 v37, v241, v37, vcc
	v_cmp_gt_f32_e32 vcc, v38, v254
	s_nop 1
	v_cndmask_b32_e32 v38, v241, v38, vcc
	v_cmp_gt_f32_e32 vcc, v39, v254
	s_nop 1
	v_cndmask_b32_e32 v39, v241, v39, vcc
	v_cmp_gt_f32_e32 vcc, v40, v254
	s_nop 1
	v_cndmask_b32_e32 v40, v241, v40, vcc
	v_cmp_gt_f32_e32 vcc, v41, v254
	s_nop 1
	v_cndmask_b32_e32 v41, v241, v41, vcc
	v_cmp_gt_f32_e32 vcc, v42, v254
	s_nop 1
	v_cndmask_b32_e32 v42, v241, v42, vcc
	v_cmp_gt_f32_e32 vcc, v43, v254
	s_nop 1
	v_cndmask_b32_e32 v43, v241, v43, vcc
	v_cmp_gt_f32_e32 vcc, v44, v254
	s_nop 1
	v_cndmask_b32_e32 v44, v241, v44, vcc
	v_cmp_gt_f32_e32 vcc, v45, v254
	s_nop 1
	v_cndmask_b32_e32 v45, v241, v45, vcc
	v_cmp_gt_f32_e32 vcc, v46, v254
	s_nop 1
	v_cndmask_b32_e32 v46, v241, v46, vcc
	v_cmp_gt_f32_e32 vcc, v47, v254
	s_nop 1
	v_cndmask_b32_e32 v47, v241, v47, vcc
	v_cmp_gt_f32_e32 vcc, v48, v254
	s_nop 1
	v_cndmask_b32_e32 v48, v241, v48, vcc
	v_cmp_gt_f32_e32 vcc, v49, v254
	s_nop 1
	v_cndmask_b32_e32 v49, v241, v49, vcc
	v_cmp_gt_f32_e32 vcc, v50, v254
	s_nop 1
	v_cndmask_b32_e32 v50, v241, v50, vcc
	v_cmp_gt_f32_e32 vcc, v51, v254
	s_nop 1
	v_cndmask_b32_e32 v51, v241, v51, vcc
	v_cmp_gt_f32_e32 vcc, v52, v254
	s_nop 1
	v_cndmask_b32_e32 v52, v241, v52, vcc
	v_cmp_gt_f32_e32 vcc, v53, v254
	s_nop 1
	v_cndmask_b32_e32 v53, v241, v53, vcc
	v_cmp_gt_f32_e32 vcc, v54, v254
	s_nop 1
	v_cndmask_b32_e32 v54, v241, v54, vcc
	v_cmp_gt_f32_e32 vcc, v55, v254
	s_nop 1
	v_cndmask_b32_e32 v55, v241, v55, vcc
	v_cmp_gt_f32_e32 vcc, v56, v254
	s_nop 1
	v_cndmask_b32_e32 v56, v241, v56, vcc
	v_cmp_gt_f32_e32 vcc, v57, v254
	s_nop 1
	v_cndmask_b32_e32 v57, v241, v57, vcc
	v_cmp_gt_f32_e32 vcc, v58, v254
	s_nop 1
	v_cndmask_b32_e32 v58, v241, v58, vcc
	v_cmp_gt_f32_e32 vcc, v59, v254
	s_nop 1
	v_cndmask_b32_e32 v59, v241, v59, vcc
	v_cmp_gt_f32_e32 vcc, v60, v254
	s_nop 1
	v_cndmask_b32_e32 v60, v241, v60, vcc
	v_cmp_gt_f32_e32 vcc, v61, v254
	s_nop 1
	v_cndmask_b32_e32 v61, v241, v61, vcc
	v_cmp_gt_f32_e32 vcc, v62, v254
	s_nop 1
	v_cndmask_b32_e32 v62, v241, v62, vcc
	v_cmp_gt_f32_e32 vcc, v63, v254
	s_nop 1
	v_cndmask_b32_e32 v63, v241, v63, vcc
	v_cmp_gt_f32_e32 vcc, v64, v254
	s_nop 1
	v_cndmask_b32_e32 v64, v241, v64, vcc
	v_cmp_gt_f32_e32 vcc, v65, v254
	s_nop 1
	v_cndmask_b32_e32 v65, v241, v65, vcc
	s_branch .Lm21_qk
